# ret_state: flat->global loads, all 20 loads per item issued up front with counted vmcnt
# speedup vs baseline: 1.0164x; 1.0164x over previous
.LBB0_131:
	s_ashr_i32 s4, s13, 7
	s_ashr_i32 s5, s4, 31
	s_lshl_b64 s[4:5], s[4:5], 12
	s_and_b32 s8, s6, 0xf80
	s_or_b32 s4, s4, s8
	v_lshl_add_u64 v[2:3], s[4:5], 0, v[34:35]
	v_mov_b64_e32 v[4:5], s[26:27]
	v_mad_u64_u32 v[18:19], s[4:5], v2, s83, v[4:5]
	v_add_u32_e32 v4, s8, v34
	v_ashrrev_i32_e32 v5, 31, v4
	v_lshlrev_b64 v[20:21], 9, v[4:5]
	v_mul_f32_e64 v4, v44, -v45
	s_mov_b32 s4, 0xc2fc0000
	v_cmp_gt_f32_e32 vcc, s4, v4
	v_mad_i32_i24 v19, v3, s83, v19
	s_lshl_b32 s36, s15, 8
	v_cndmask_b32_e32 v5, 0, v201, vcc
	v_fma_f32 v5, v44, -v45, v5
	v_exp_f32_e32 v5, v5
	v_lshl_add_u64 v[2:3], v[18:19], 0, s[36:37]
	v_cndmask_b32_e32 v4, 0, v200, vcc
	v_lshl_add_u64 v[6:7], v[2:3], 0, v[0:1]
	v_ldexp_f32 v4, v5, v4
	v_lshl_add_u64 v[20:21], v[36:37], 0, v[20:21]
	v_mul_f32_e32 v22, 0x3db504f3, v4
	global_load_dwordx4 v[10:13], v[6:7], off offset:1024
	global_load_dwordx4 v[2:5], v[6:7], off offset:1040
	global_load_dwordx4 v[14:17], v[6:7], off offset:1152
	s_nop 0
	global_load_dwordx4 v[6:9], v[6:7], off offset:1168
	s_lshl_b32 s36, s15, 9
	global_load_dwordx4 v[24:27], v[20:21], off
	v_mov_b32_e32 v43, v1
	global_load_dwordx4 v[114:117], v[20:21], off offset:16
	global_load_dwordx4 v[118:121], v[20:21], off offset:32
	global_load_dwordx4 v[122:125], v[20:21], off offset:48
	global_load_dwordx4 v[126:129], v[20:21], off offset:64
	global_load_dwordx4 v[130:133], v[20:21], off offset:80
	global_load_dwordx4 v[134:137], v[20:21], off offset:96
	global_load_dwordx4 v[138:141], v[20:21], off offset:112
	v_lshl_add_u64 v[142:143], v[18:19], 0, s[36:37]
	v_lshl_add_u64 v[142:143], v[142:143], 0, v[42:43]
	global_load_dwordx4 v[148:151], v[142:143], off offset:2048
	global_load_dwordx4 v[152:155], v[142:143], off offset:2064
	global_load_dwordx4 v[182:185], v[142:143], off offset:2080
	global_load_dwordx4 v[186:189], v[142:143], off offset:2096
	global_load_dwordx4 v[190:193], v[142:143], off offset:2112
	global_load_dwordx4 v[210:213], v[142:143], off offset:2128
	global_load_dwordx4 v[214:217], v[142:143], off offset:2144
	global_load_dwordx4 v[218:221], v[142:143], off offset:2160
	s_waitcnt vmcnt(15)
	v_lshlrev_b32_e32 v23, 16, v10
	v_and_b32_e32 v28, 0xffff0000, v10
	v_lshlrev_b32_e32 v29, 16, v14
	v_and_b32_e32 v14, 0xffff0000, v14
	v_mul_f32_e32 v10, v25, v29
	v_fma_f32 v10, v24, v23, -v10
	v_mul_f32_e32 v24, v24, v29
	v_mul_f32_e32 v30, v27, v14
	v_fmac_f32_e32 v24, v25, v23
	v_mul_f32_e32 v14, v26, v14
	v_mul_f32_e32 v10, v22, v10
	v_fma_f32 v30, v26, v28, -v30
	v_mul_f32_e32 v23, v22, v24
	v_fmac_f32_e32 v14, v27, v28
	v_mul_f32_e32 v30, v22, v30
	v_cvt_pk_bf16_f32 v10, v10, v30
	v_mul_f32_e32 v14, v22, v14
	v_cvt_pk_bf16_f32 v23, v23, v14
	v_lshlrev_b32_e32 v28, 16, v15
	v_and_b32_e32 v15, 0xffff0000, v15
	v_lshlrev_b32_e32 v14, 16, v11
	v_and_b32_e32 v11, 0xffff0000, v11
	s_waitcnt vmcnt(14)
	v_mul_f32_e32 v29, v115, v28
	v_mul_f32_e32 v30, v117, v15
	v_mul_f32_e32 v15, v116, v15
	v_fma_f32 v29, v114, v14, -v29
	v_mul_f32_e32 v114, v114, v28
	v_fmac_f32_e32 v15, v117, v11
	v_mul_f32_e32 v29, v22, v29
	v_fma_f32 v30, v116, v11, -v30
	v_fmac_f32_e32 v114, v115, v14
	v_mul_f32_e32 v11, v22, v15
	v_mul_f32_e32 v30, v22, v30
	v_cvt_pk_bf16_f32 v29, v29, v30
	v_mul_f32_e32 v14, v22, v114
	v_cvt_pk_bf16_f32 v11, v14, v11
	v_lshlrev_b32_e32 v15, 16, v16
	v_lshlrev_b32_e32 v14, 16, v12
	v_and_b32_e32 v16, 0xffff0000, v16
	v_and_b32_e32 v12, 0xffff0000, v12
	s_waitcnt vmcnt(13)
	v_mul_f32_e32 v28, v119, v15
	v_mul_f32_e32 v15, v118, v15
	v_fmac_f32_e32 v15, v119, v14
	v_fma_f32 v28, v118, v14, -v28
	v_mul_f32_e32 v30, v121, v16
	v_mul_f32_e32 v14, v22, v15
	v_mul_f32_e32 v15, v120, v16
	v_mul_f32_e32 v28, v22, v28
	v_fma_f32 v30, v120, v12, -v30
	v_fmac_f32_e32 v15, v121, v12
	v_mul_f32_e32 v30, v22, v30
	v_cvt_pk_bf16_f32 v28, v28, v30
	v_mul_f32_e32 v12, v22, v15
	v_cvt_pk_bf16_f32 v16, v14, v12
	v_lshlrev_b32_e32 v14, 16, v17
	v_lshlrev_b32_e32 v12, 16, v13
	v_and_b32_e32 v15, 0xffff0000, v17
	v_and_b32_e32 v13, 0xffff0000, v13
	s_waitcnt vmcnt(12)
	v_mul_f32_e32 v17, v123, v14
	v_mul_f32_e32 v14, v122, v14
	v_fmac_f32_e32 v14, v123, v12
	v_fma_f32 v17, v122, v12, -v17
	v_mul_f32_e32 v12, v22, v14
	v_mul_f32_e32 v14, v124, v15
	v_mul_f32_e32 v30, v125, v15
	v_fmac_f32_e32 v14, v125, v13
	v_mul_f32_e32 v17, v22, v17
	v_fma_f32 v30, v124, v13, -v30
	v_mul_f32_e32 v13, v22, v14
	v_mul_f32_e32 v30, v22, v30
	v_cvt_pk_bf16_f32 v17, v17, v30
	v_cvt_pk_bf16_f32 v122, v12, v13
	v_lshlrev_b32_e32 v26, 16, v6
	v_lshlrev_b32_e32 v25, 16, v2
	v_and_b32_e32 v6, 0xffff0000, v6
	v_and_b32_e32 v2, 0xffff0000, v2
	s_waitcnt vmcnt(11)
	v_mul_f32_e32 v27, v127, v26
	v_fma_f32 v27, v126, v25, -v27
	v_mul_f32_e32 v30, v129, v6
	v_mul_f32_e32 v126, v126, v26
	v_mul_f32_e32 v6, v128, v6
	v_fmac_f32_e32 v126, v127, v25
	v_fmac_f32_e32 v6, v129, v2
	v_mul_f32_e32 v27, v22, v27
	v_fma_f32 v30, v128, v2, -v30
	v_mul_f32_e32 v126, v22, v126
	v_mul_f32_e32 v2, v22, v6
	v_mul_f32_e32 v30, v22, v30
	v_cvt_pk_bf16_f32 v27, v27, v30
	v_cvt_pk_bf16_f32 v2, v126, v2
	v_lshlrev_b32_e32 v25, 16, v7
	v_and_b32_e32 v7, 0xffff0000, v7
	v_lshlrev_b32_e32 v6, 16, v3
	v_and_b32_e32 v3, 0xffff0000, v3
	s_waitcnt vmcnt(10)
	v_mul_f32_e32 v26, v131, v25
	v_mul_f32_e32 v30, v133, v7
	v_mul_f32_e32 v7, v132, v7
	v_fma_f32 v26, v130, v6, -v26
	v_mul_f32_e32 v130, v130, v25
	v_fmac_f32_e32 v7, v133, v3
	v_mul_f32_e32 v26, v22, v26
	v_fma_f32 v30, v132, v3, -v30
	v_fmac_f32_e32 v130, v131, v6
	v_mul_f32_e32 v3, v22, v7
	v_mul_f32_e32 v30, v22, v30
	v_cvt_pk_bf16_f32 v26, v26, v30
	v_mul_f32_e32 v6, v22, v130
	v_cvt_pk_bf16_f32 v3, v6, v3
	v_lshlrev_b32_e32 v7, 16, v8
	v_lshlrev_b32_e32 v6, 16, v4
	v_and_b32_e32 v8, 0xffff0000, v8
	v_and_b32_e32 v4, 0xffff0000, v4
	s_waitcnt vmcnt(9)
	v_mul_f32_e32 v25, v135, v7
	v_mul_f32_e32 v7, v134, v7
	v_fmac_f32_e32 v7, v135, v6
	v_fma_f32 v25, v134, v6, -v25
	v_mul_f32_e32 v6, v22, v7
	v_mul_f32_e32 v7, v136, v8
	v_mul_f32_e32 v30, v137, v8
	v_fmac_f32_e32 v7, v137, v4
	v_mul_f32_e32 v25, v22, v25
	v_fma_f32 v30, v136, v4, -v30
	v_mul_f32_e32 v4, v22, v7
	v_mul_f32_e32 v30, v22, v30
	v_cvt_pk_bf16_f32 v25, v25, v30
	v_cvt_pk_bf16_f32 v4, v6, v4
	v_lshlrev_b32_e32 v7, 16, v9
	v_lshlrev_b32_e32 v6, 16, v5
	v_and_b32_e32 v8, 0xffff0000, v9
	v_and_b32_e32 v5, 0xffff0000, v5
	s_waitcnt vmcnt(8)
	v_mul_f32_e32 v9, v139, v7
	v_mul_f32_e32 v7, v138, v7
	v_fmac_f32_e32 v7, v139, v6
	v_fma_f32 v9, v138, v6, -v9
	v_mul_f32_e32 v6, v22, v7
	v_mul_f32_e32 v7, v140, v8
	v_mul_f32_e32 v20, v141, v8
	v_fmac_f32_e32 v7, v141, v5
	v_mul_f32_e32 v9, v22, v9
	v_fma_f32 v20, v140, v5, -v20
	v_mul_f32_e32 v5, v22, v7
	v_mul_f32_e32 v20, v22, v20
	v_cvt_pk_bf16_f32 v9, v9, v20
	v_cvt_pk_bf16_f32 v5, v6, v5
	ds_write_b16 v46, v10
	ds_write_b16_d16_hi v46, v10 offset:272
	ds_write_b16 v46, v23 offset:17408
	ds_write_b16_d16_hi v46, v23 offset:17680
	ds_write_b16 v46, v29 offset:544
	ds_write_b16_d16_hi v46, v29 offset:816
	ds_write_b16 v46, v11 offset:17952
	ds_write_b16_d16_hi v46, v11 offset:18224
	ds_write_b16 v46, v28 offset:1088
	ds_write_b16_d16_hi v46, v28 offset:1360
	ds_write_b16 v46, v16 offset:18496
	ds_write_b16_d16_hi v46, v16 offset:18768
	ds_write_b16 v46, v17 offset:1632
	ds_write_b16_d16_hi v46, v17 offset:1904
	ds_write_b16 v46, v122 offset:19040
	ds_write_b16_d16_hi v46, v122 offset:19312
	ds_write_b16 v46, v27 offset:2176
	ds_write_b16_d16_hi v46, v27 offset:2448
	ds_write_b16 v46, v2 offset:19584
	ds_write_b16_d16_hi v46, v2 offset:19856
	ds_write_b16 v46, v26 offset:2720
	ds_write_b16_d16_hi v46, v26 offset:2992
	ds_write_b16 v46, v3 offset:20128
	ds_write_b16_d16_hi v46, v3 offset:20400
	ds_write_b16 v46, v25 offset:3264
	ds_write_b16_d16_hi v46, v25 offset:3536
	ds_write_b16 v46, v4 offset:20672
	ds_write_b16_d16_hi v46, v4 offset:20944
	ds_write_b16 v46, v9 offset:3808
	ds_write_b16_d16_hi v46, v9 offset:4080
	ds_write_b16 v46, v5 offset:21216
	ds_write_b16_d16_hi v46, v5 offset:21488
	s_waitcnt vmcnt(7)
	ds_write_b16 v47, v148 offset:34816
	ds_write_b16_d16_hi v47, v148 offset:35088
	ds_write_b16 v47, v149 offset:35360
	ds_write_b16_d16_hi v47, v149 offset:35632
	ds_write_b16 v47, v150 offset:35904
	ds_write_b16_d16_hi v47, v150 offset:36176
	ds_write_b16 v47, v151 offset:36448
	ds_write_b16_d16_hi v47, v151 offset:36720
	s_waitcnt vmcnt(6)
	ds_write_b16 v47, v152 offset:36992
	ds_write_b16_d16_hi v47, v152 offset:37264
	ds_write_b16 v47, v153 offset:37536
	ds_write_b16_d16_hi v47, v153 offset:37808
	ds_write_b16 v47, v154 offset:38080
	ds_write_b16_d16_hi v47, v154 offset:38352
	ds_write_b16 v47, v155 offset:38624
	ds_write_b16_d16_hi v47, v155 offset:38896
	s_waitcnt vmcnt(5)
	ds_write_b16 v47, v182 offset:39168
	ds_write_b16_d16_hi v47, v182 offset:39440
	ds_write_b16 v47, v183 offset:39712
	ds_write_b16_d16_hi v47, v183 offset:39984
	ds_write_b16 v47, v184 offset:40256
	ds_write_b16_d16_hi v47, v184 offset:40528
	ds_write_b16 v47, v185 offset:40800
	ds_write_b16_d16_hi v47, v185 offset:41072
	s_waitcnt vmcnt(4)
	ds_write_b16 v47, v186 offset:41344
	ds_write_b16_d16_hi v47, v186 offset:41616
	ds_write_b16 v47, v187 offset:41888
	ds_write_b16_d16_hi v47, v187 offset:42160
	ds_write_b16 v47, v188 offset:42432
	ds_write_b16_d16_hi v47, v188 offset:42704
	ds_write_b16 v47, v189 offset:42976
	ds_write_b16_d16_hi v47, v189 offset:43248
	s_waitcnt vmcnt(3)
	ds_write_b16 v47, v190 offset:43520
	ds_write_b16_d16_hi v47, v190 offset:43792
	ds_write_b16 v47, v191 offset:44064
	ds_write_b16_d16_hi v47, v191 offset:44336
	ds_write_b16 v47, v192 offset:44608
	ds_write_b16_d16_hi v47, v192 offset:44880
	ds_write_b16 v47, v193 offset:45152
	ds_write_b16_d16_hi v47, v193 offset:45424
	s_waitcnt vmcnt(2)
	ds_write_b16 v47, v210 offset:45696
	ds_write_b16_d16_hi v47, v210 offset:45968
	ds_write_b16 v47, v211 offset:46240
	ds_write_b16_d16_hi v47, v211 offset:46512
	ds_write_b16 v47, v212 offset:46784
	ds_write_b16_d16_hi v47, v212 offset:47056
	ds_write_b16 v47, v213 offset:47328
	ds_write_b16_d16_hi v47, v213 offset:47600
	s_waitcnt vmcnt(1)
	ds_write_b16 v47, v214 offset:47872
	ds_write_b16_d16_hi v47, v214 offset:48144
	ds_write_b16 v47, v215 offset:48416
	ds_write_b16_d16_hi v47, v215 offset:48688
	ds_write_b16 v47, v216 offset:48960
	ds_write_b16_d16_hi v47, v216 offset:49232
	ds_write_b16 v47, v217 offset:49504
	ds_write_b16_d16_hi v47, v217 offset:49776
	s_waitcnt vmcnt(0)
	ds_write_b16 v47, v218 offset:50048
	ds_write_b16_d16_hi v47, v218 offset:50320
	ds_write_b16 v47, v219 offset:50592
	ds_write_b16_d16_hi v47, v219 offset:50864
	ds_write_b16 v47, v220 offset:51136
	ds_write_b16_d16_hi v47, v220 offset:51408
	ds_write_b16 v47, v221 offset:51680
	ds_write_b16_d16_hi v47, v221 offset:51952
	s_waitcnt lgkmcnt(0)
	s_barrier
	ds_read_b128 v[2:5], v49 offset:34816
	ds_read_b128 v[6:9], v49 offset:39168
	ds_read_b128 v[10:13], v50
	ds_read_b128 v[18:21], v50 offset:4352
	ds_read_b128 v[26:29], v50 offset:8704
	ds_read_b128 v[54:57], v50 offset:13056
	ds_read_b128 v[62:65], v50 offset:17408
	ds_read_b128 v[70:73], v50 offset:21760
	ds_read_b128 v[78:81], v50 offset:26112
	ds_read_b128 v[86:89], v50 offset:30464
	s_waitcnt lgkmcnt(7)
	v_mfma_f32_16x16x32_bf16 v[14:17], v[10:13], v[2:5], 0
	v_mul_f32_e32 v43, 0x43000000, v44
	v_cmp_gt_f32_e32 vcc, s4, v43
	s_and_b64 s[4:5], vcc, exec
	v_mfma_f32_16x16x32_bf16 v[10:13], v[10:13], v[6:9], 0
	v_cndmask_b32_e32 v43, 0, v201, vcc
	v_fmac_f32_e32 v43, 0x43000000, v44
	v_exp_f32_e32 v43, v43
	s_waitcnt lgkmcnt(6)
	v_mfma_f32_16x16x32_bf16 v[22:25], v[18:21], v[2:5], 0
	s_cselect_b32 s4, 0xffffffc0, 0
	s_add_i32 s13, s13, s14
	v_ldexp_f32 v44, v43, s4
	v_mfma_f32_16x16x32_bf16 v[18:21], v[18:21], v[6:9], 0
	s_mov_b32 s4, 0x19380000
	s_add_i32 s6, s6, s7
	s_cmpk_gt_i32 s13, 0x1ff
	s_waitcnt lgkmcnt(5)
	v_mfma_f32_16x16x32_bf16 v[30:33], v[26:29], v[2:5], 0
	v_mfma_f32_16x16x32_bf16 v[26:29], v[26:29], v[6:9], 0
	s_waitcnt lgkmcnt(4)
	v_mfma_f32_16x16x32_bf16 v[58:61], v[54:57], v[2:5], 0
	v_mfma_f32_16x16x32_bf16 v[54:57], v[54:57], v[6:9], 0
	s_waitcnt lgkmcnt(3)
	v_mfma_f32_16x16x32_bf16 v[66:69], v[62:65], v[2:5], 0
	v_mfma_f32_16x16x32_bf16 v[62:65], v[62:65], v[6:9], 0
	s_waitcnt lgkmcnt(2)
	v_mfma_f32_16x16x32_bf16 v[74:77], v[70:73], v[2:5], 0
	v_mfma_f32_16x16x32_bf16 v[70:73], v[70:73], v[6:9], 0
	s_waitcnt lgkmcnt(1)
	v_mfma_f32_16x16x32_bf16 v[82:85], v[78:81], v[2:5], 0
	v_mfma_f32_16x16x32_bf16 v[78:81], v[78:81], v[6:9], 0
	s_waitcnt lgkmcnt(0)
	v_mfma_f32_16x16x32_bf16 v[2:5], v[86:89], v[2:5], 0
	v_mfma_f32_16x16x32_bf16 v[6:9], v[86:89], v[6:9], 0
	ds_read_b128 v[86:89], v49 offset:34880
	ds_read_b128 v[90:93], v49 offset:39232
	ds_read_b128 v[94:97], v50 offset:64
	s_waitcnt lgkmcnt(0)
	v_mfma_f32_16x16x32_bf16 v[14:17], v[94:97], v[86:89], v[14:17]
	v_mfma_f32_16x16x32_bf16 v[10:13], v[94:97], v[90:93], v[10:13]
	ds_read_b128 v[94:97], v50 offset:4416
	s_waitcnt lgkmcnt(0)
	v_mfma_f32_16x16x32_bf16 v[22:25], v[94:97], v[86:89], v[22:25]
	v_mfma_f32_16x16x32_bf16 v[18:21], v[94:97], v[90:93], v[18:21]
	ds_read_b128 v[94:97], v50 offset:8768
	s_waitcnt lgkmcnt(0)
	v_mfma_f32_16x16x32_bf16 v[30:33], v[94:97], v[86:89], v[30:33]
	v_mfma_f32_16x16x32_bf16 v[26:29], v[94:97], v[90:93], v[26:29]
	ds_read_b128 v[94:97], v50 offset:13120
	s_waitcnt lgkmcnt(0)
	v_mfma_f32_16x16x32_bf16 v[58:61], v[94:97], v[86:89], v[58:61]
	v_mfma_f32_16x16x32_bf16 v[54:57], v[94:97], v[90:93], v[54:57]
	ds_read_b128 v[94:97], v50 offset:17472
	s_waitcnt lgkmcnt(0)
	v_mfma_f32_16x16x32_bf16 v[66:69], v[94:97], v[86:89], v[66:69]
	v_mfma_f32_16x16x32_bf16 v[62:65], v[94:97], v[90:93], v[62:65]
	ds_read_b128 v[94:97], v50 offset:21824
	s_waitcnt lgkmcnt(0)
	v_mfma_f32_16x16x32_bf16 v[74:77], v[94:97], v[86:89], v[74:77]
	v_mfma_f32_16x16x32_bf16 v[70:73], v[94:97], v[90:93], v[70:73]
	ds_read_b128 v[94:97], v50 offset:26176
	s_waitcnt lgkmcnt(0)
	v_mfma_f32_16x16x32_bf16 v[82:85], v[94:97], v[86:89], v[82:85]
	v_mfma_f32_16x16x32_bf16 v[78:81], v[94:97], v[90:93], v[78:81]
	ds_read_b128 v[94:97], v50 offset:30528
	s_waitcnt lgkmcnt(0)
	v_mfma_f32_16x16x32_bf16 v[2:5], v[94:97], v[86:89], v[2:5]
	v_mfma_f32_16x16x32_bf16 v[6:9], v[94:97], v[90:93], v[6:9]
	ds_read_b128 v[86:89], v49 offset:34944
	ds_read_b128 v[90:93], v49 offset:39296
	ds_read_b128 v[94:97], v50 offset:128
	s_waitcnt lgkmcnt(0)
	v_mfma_f32_16x16x32_bf16 v[14:17], v[94:97], v[86:89], v[14:17]
	v_mfma_f32_16x16x32_bf16 v[10:13], v[94:97], v[90:93], v[10:13]
	ds_read_b128 v[94:97], v50 offset:4480
	s_waitcnt lgkmcnt(0)
	v_mfma_f32_16x16x32_bf16 v[22:25], v[94:97], v[86:89], v[22:25]
	v_mfma_f32_16x16x32_bf16 v[18:21], v[94:97], v[90:93], v[18:21]
	ds_read_b128 v[94:97], v50 offset:8832
	s_waitcnt lgkmcnt(0)
	v_mfma_f32_16x16x32_bf16 v[30:33], v[94:97], v[86:89], v[30:33]
	v_mfma_f32_16x16x32_bf16 v[26:29], v[94:97], v[90:93], v[26:29]
	ds_read_b128 v[94:97], v50 offset:13184
	s_waitcnt lgkmcnt(0)
	v_mfma_f32_16x16x32_bf16 v[58:61], v[94:97], v[86:89], v[58:61]
	v_mfma_f32_16x16x32_bf16 v[54:57], v[94:97], v[90:93], v[54:57]
	ds_read_b128 v[94:97], v50 offset:17536
	s_waitcnt lgkmcnt(0)
	v_mfma_f32_16x16x32_bf16 v[66:69], v[94:97], v[86:89], v[66:69]
	v_mfma_f32_16x16x32_bf16 v[62:65], v[94:97], v[90:93], v[62:65]
	ds_read_b128 v[94:97], v50 offset:21888
	s_waitcnt lgkmcnt(0)
	v_mfma_f32_16x16x32_bf16 v[74:77], v[94:97], v[86:89], v[74:77]
	v_mfma_f32_16x16x32_bf16 v[70:73], v[94:97], v[90:93], v[70:73]
	ds_read_b128 v[94:97], v50 offset:26240
	s_waitcnt lgkmcnt(0)
	v_mfma_f32_16x16x32_bf16 v[82:85], v[94:97], v[86:89], v[82:85]
	v_mfma_f32_16x16x32_bf16 v[78:81], v[94:97], v[90:93], v[78:81]
	ds_read_b128 v[94:97], v50 offset:30592
	s_waitcnt lgkmcnt(0)
	v_mfma_f32_16x16x32_bf16 v[86:89], v[94:97], v[86:89], v[2:5]
	v_mfma_f32_16x16x32_bf16 v[90:93], v[94:97], v[90:93], v[6:9]
	ds_read_b128 v[94:97], v49 offset:35008
	ds_read_b128 v[98:101], v49 offset:39360
	ds_read_b128 v[2:5], v50 offset:192
	ds_read_b128 v[6:9], v50 offset:4544
	s_waitcnt lgkmcnt(1)
	v_mfma_f32_16x16x32_bf16 v[102:105], v[2:5], v[94:97], v[14:17]
	s_nop 2
	ds_read_b128 v[14:17], v50 offset:13248
	v_mfma_f32_16x16x32_bf16 v[2:5], v[2:5], v[98:101], v[10:13]
	s_nop 2
	ds_read_b128 v[10:13], v50 offset:8896
	s_waitcnt lgkmcnt(2)
	v_mfma_f32_16x16x32_bf16 v[106:109], v[6:9], v[94:97], v[22:25]
	s_nop 1
	v_mul_f32_e64 v4, v44, v4
	v_mul_f32_e64 v5, v44, v5
	v_pk_mul_f32 v[2:3], v[44:45], v[2:3] op_sel_hi:[0,1]
	v_mfma_f32_16x16x32_bf16 v[6:9], v[6:9], v[98:101], v[18:21]
	ds_read_b128 v[22:25], v50 offset:21952
	s_nop 1
	ds_read_b128 v[18:21], v50 offset:17600
	s_waitcnt lgkmcnt(2)
	v_mfma_f32_16x16x32_bf16 v[110:113], v[10:13], v[94:97], v[30:33]
	s_nop 1
	v_mul_f32_e64 v6, v44, v6
	v_mul_f32_e64 v7, v44, v7
	v_mfma_f32_16x16x32_bf16 v[10:13], v[10:13], v[98:101], v[26:29]
	ds_read_b128 v[30:33], v50 offset:30656
	s_nop 1
	ds_read_b128 v[26:29], v50 offset:26304
	v_mfma_f32_16x16x32_bf16 v[58:61], v[14:17], v[94:97], v[58:61]
	v_mfma_f32_16x16x32_bf16 v[14:17], v[14:17], v[98:101], v[54:57]
	s_waitcnt lgkmcnt(2)
	v_mfma_f32_16x16x32_bf16 v[54:57], v[18:21], v[94:97], v[66:69]
	s_nop 4
	v_mul_f32_e64 v58, v44, v58
	v_mul_f32_e64 v59, v44, v59
	v_pk_mul_f32 v[60:61], v[44:45], v[60:61] op_sel_hi:[0,1]
	v_mfma_f32_16x16x32_bf16 v[18:21], v[18:21], v[98:101], v[62:65]
	v_mfma_f32_16x16x32_bf16 v[62:65], v[22:25], v[94:97], v[74:77]
	v_mul_f32_e64 v56, v44, v56
	v_mul_f32_e64 v57, v44, v57
	v_pk_mul_f32 v[54:55], v[44:45], v[54:55] op_sel_hi:[0,1]
	v_lshl_add_u64 v[74:75], v[38:39], 0, v[52:53]
	s_waitcnt lgkmcnt(0)
	v_mfma_f32_16x16x32_bf16 v[66:69], v[26:29], v[94:97], v[82:85]
	v_add_co_u32_e32 v74, vcc, s4, v74
	v_pk_mul_f32 v[76:77], v[44:45], v[104:105] op_sel_hi:[0,1]
	v_mfma_f32_16x16x32_bf16 v[26:29], v[26:29], v[98:101], v[78:81]
	v_addc_co_u32_e32 v75, vcc, 0, v75, vcc
	v_lshl_add_u64 v[38:39], v[38:39], 0, s[0:1]
	s_nop 0
	v_pk_mul_f32 v[78:79], v[44:45], v[102:103] op_sel_hi:[0,1]
	v_cvt_pk_bf16_f32 v78, v78, v79
	v_cvt_pk_bf16_f32 v79, v76, v77
	flat_store_dwordx2 v[74:75], v[78:79]
	v_pk_mul_f32 v[78:79], v[44:45], v[106:107] op_sel_hi:[0,1]
	v_pk_mul_f32 v[76:77], v[44:45], v[108:109] op_sel_hi:[0,1]
	v_cvt_pk_bf16_f32 v78, v78, v79
	v_cvt_pk_bf16_f32 v79, v76, v77
	flat_store_dwordx2 v[74:75], v[78:79] offset:32
	v_pk_mul_f32 v[78:79], v[44:45], v[110:111] op_sel_hi:[0,1]
	v_mfma_f32_16x16x32_bf16 v[22:25], v[22:25], v[98:101], v[70:73]
	v_mul_f32_e64 v76, v44, v112
	v_mul_f32_e64 v77, v44, v113
	v_cvt_pk_bf16_f32 v78, v78, v79
	v_cvt_pk_bf16_f32 v79, v76, v77
	v_mfma_f32_16x16x32_bf16 v[70:73], v[30:33], v[94:97], v[86:89]
	flat_store_dwordx2 v[74:75], v[78:79] offset:64
	v_cvt_pk_bf16_f32 v58, v58, v59
	v_cvt_pk_bf16_f32 v59, v60, v61
	flat_store_dwordx2 v[74:75], v[58:59] offset:96
	v_cvt_pk_bf16_f32 v54, v54, v55
	v_cvt_pk_bf16_f32 v55, v56, v57
	v_pk_mul_f32 v[56:57], v[44:45], v[62:63] op_sel_hi:[0,1]
	flat_store_dwordx2 v[74:75], v[54:55] offset:128
	v_pk_mul_f32 v[54:55], v[44:45], v[64:65] op_sel_hi:[0,1]
	v_cvt_pk_bf16_f32 v56, v56, v57
	v_cvt_pk_bf16_f32 v57, v54, v55
	flat_store_dwordx2 v[74:75], v[56:57] offset:160
	v_pk_mul_f32 v[56:57], v[44:45], v[66:67] op_sel_hi:[0,1]
	v_pk_mul_f32 v[54:55], v[44:45], v[68:69] op_sel_hi:[0,1]
	v_cvt_pk_bf16_f32 v56, v56, v57
	v_cvt_pk_bf16_f32 v57, v54, v55
	flat_store_dwordx2 v[74:75], v[56:57] offset:192
	v_pk_mul_f32 v[54:55], v[44:45], v[72:73] op_sel_hi:[0,1]
	v_pk_mul_f32 v[56:57], v[44:45], v[70:71] op_sel_hi:[0,1]
	v_cvt_pk_bf16_f32 v56, v56, v57
	v_cvt_pk_bf16_f32 v57, v54, v55
	v_lshl_add_u64 v[54:55], v[40:41], 0, v[52:53]
	flat_store_dwordx2 v[74:75], v[56:57] offset:224
	v_cvt_pk_bf16_f32 v2, v2, v3
	v_cvt_pk_bf16_f32 v3, v4, v5
	v_add_co_u32_e32 v4, vcc, s4, v54
	v_mfma_f32_16x16x32_bf16 v[30:33], v[30:33], v[98:101], v[90:93]
	s_nop 0
	v_addc_co_u32_e32 v5, vcc, 0, v55, vcc
	flat_store_dwordx2 v[4:5], v[2:3]
	v_pk_mul_f32 v[2:3], v[44:45], v[8:9] op_sel_hi:[0,1]
	v_cvt_pk_bf16_f32 v6, v6, v7
	v_cvt_pk_bf16_f32 v7, v2, v3
	flat_store_dwordx2 v[4:5], v[6:7] offset:32
	v_pk_mul_f32 v[6:7], v[44:45], v[10:11] op_sel_hi:[0,1]
	v_pk_mul_f32 v[2:3], v[44:45], v[12:13] op_sel_hi:[0,1]
	v_cvt_pk_bf16_f32 v6, v6, v7
	v_cvt_pk_bf16_f32 v7, v2, v3
	flat_store_dwordx2 v[4:5], v[6:7] offset:64
	v_pk_mul_f32 v[6:7], v[44:45], v[14:15] op_sel_hi:[0,1]
	v_pk_mul_f32 v[2:3], v[44:45], v[16:17] op_sel_hi:[0,1]
	v_cvt_pk_bf16_f32 v6, v6, v7
	v_cvt_pk_bf16_f32 v7, v2, v3
	flat_store_dwordx2 v[4:5], v[6:7] offset:96
	v_pk_mul_f32 v[6:7], v[44:45], v[18:19] op_sel_hi:[0,1]
	v_pk_mul_f32 v[2:3], v[44:45], v[20:21] op_sel_hi:[0,1]
	v_cvt_pk_bf16_f32 v6, v6, v7
	v_cvt_pk_bf16_f32 v7, v2, v3
	flat_store_dwordx2 v[4:5], v[6:7] offset:128
	v_pk_mul_f32 v[6:7], v[44:45], v[22:23] op_sel_hi:[0,1]
	v_pk_mul_f32 v[2:3], v[44:45], v[24:25] op_sel_hi:[0,1]
	v_cvt_pk_bf16_f32 v6, v6, v7
	v_cvt_pk_bf16_f32 v7, v2, v3
	flat_store_dwordx2 v[4:5], v[6:7] offset:160
	v_pk_mul_f32 v[6:7], v[44:45], v[26:27] op_sel_hi:[0,1]
	v_pk_mul_f32 v[2:3], v[44:45], v[28:29] op_sel_hi:[0,1]
	v_cvt_pk_bf16_f32 v6, v6, v7
	v_cvt_pk_bf16_f32 v7, v2, v3
	flat_store_dwordx2 v[4:5], v[6:7] offset:192
	v_pk_mul_f32 v[6:7], v[44:45], v[30:31] op_sel_hi:[0,1]
	v_lshl_add_u64 v[40:41], v[40:41], 0, s[0:1]
	v_pk_mul_f32 v[2:3], v[44:45], v[32:33] op_sel_hi:[0,1]
	v_cvt_pk_bf16_f32 v6, v6, v7
	v_cvt_pk_bf16_f32 v7, v2, v3
	flat_store_dwordx2 v[4:5], v[6:7] offset:224
	s_waitcnt lgkmcnt(0)
	s_barrier
	s_cbranch_scc1 .LBB0_138
